# prompt attention: V fragment LDS reads hoisted ahead of the exp section; a single vmcnt(0) before the next-tile K register copies replaces the per-tile wait before PV (no ordering assumption between L
# baseline (speedup 1.0000x reference)
.LBB0_531:
	s_lshl_b32 s2, s21, 12
	s_add_i32 s2, s7, s2
	v_add3_u32 v230, s2, v201, v200
	v_add3_u32 v231, s2, v202, v200
	v_add3_u32 v232, s2, v203, v200
	v_add3_u32 v233, s2, v204, v200
	ds_read_b64_tr_b16 v[214:215], v230
	ds_read_b64_tr_b16 v[216:217], v230 offset:2048
	ds_read_b64_tr_b16 v[218:219], v231
	ds_read_b64_tr_b16 v[220:221], v231 offset:2048
	ds_read_b64_tr_b16 v[222:223], v232
	ds_read_b64_tr_b16 v[224:225], v232 offset:2048
	ds_read_b64_tr_b16 v[226:227], v233
	ds_read_b64_tr_b16 v[228:229], v233 offset:2048
	s_andn2_b64 vcc, exec, s[14:15]
	s_mov_b64 s[2:3], -1
	s_cbranch_vccnz .LBB0_533
	v_pk_add_f32 v[142:143], v[142:143], v[208:209] op_sel:[0,1] op_sel_hi:[1,1] neg_lo:[0,1] neg_hi:[0,1]
	v_pk_add_f32 v[144:145], v[144:145], v[208:209] op_sel:[0,1] op_sel_hi:[1,1] neg_lo:[0,1] neg_hi:[0,1]
	v_pk_add_f32 v[138:139], v[138:139], v[208:209] op_sel:[0,1] op_sel_hi:[1,1] neg_lo:[0,1] neg_hi:[0,1]
	v_pk_add_f32 v[140:141], v[140:141], v[208:209] op_sel:[0,1] op_sel_hi:[1,1] neg_lo:[0,1] neg_hi:[0,1]
	v_exp_f32_e32 v147, v142
	v_exp_f32_e32 v149, v143
	v_pk_add_f32 v[134:135], v[134:135], v[208:209] op_sel_hi:[1,0] neg_lo:[0,1] neg_hi:[0,1]
	v_exp_f32_e32 v159, v144
	v_exp_f32_e32 v161, v145
	v_pk_add_f32 v[136:137], v[136:137], v[208:209] op_sel_hi:[1,0] neg_lo:[0,1] neg_hi:[0,1]
	v_exp_f32_e32 v163, v138
	v_exp_f32_e32 v165, v139
	v_pk_add_f32 v[130:131], v[130:131], v[208:209] op_sel_hi:[1,0] neg_lo:[0,1] neg_hi:[0,1]
	v_exp_f32_e32 v167, v140
	v_exp_f32_e32 v169, v141
	v_pk_add_f32 v[132:133], v[132:133], v[208:209] op_sel_hi:[1,0] neg_lo:[0,1] neg_hi:[0,1]
	v_exp_f32_e32 v146, v134
	v_exp_f32_e32 v148, v135
	v_pk_add_f32 v[126:127], v[126:127], v[206:207] op_sel:[0,1] op_sel_hi:[1,1] neg_lo:[0,1] neg_hi:[0,1]
	v_exp_f32_e32 v158, v136
	v_exp_f32_e32 v160, v137
	v_pk_add_f32 v[128:129], v[128:129], v[206:207] op_sel:[0,1] op_sel_hi:[1,1] neg_lo:[0,1] neg_hi:[0,1]
	v_exp_f32_e32 v162, v130
	v_exp_f32_e32 v164, v131
	v_pk_add_f32 v[122:123], v[122:123], v[206:207] op_sel:[0,1] op_sel_hi:[1,1] neg_lo:[0,1] neg_hi:[0,1]
	v_exp_f32_e32 v166, v132
	v_exp_f32_e32 v168, v133
	v_pk_add_f32 v[124:125], v[124:125], v[206:207] op_sel:[0,1] op_sel_hi:[1,1] neg_lo:[0,1] neg_hi:[0,1]
	v_exp_f32_e32 v211, v126
	v_exp_f32_e32 v173, v127
	v_pk_add_f32 v[118:119], v[118:119], v[206:207] op_sel_hi:[1,0] neg_lo:[0,1] neg_hi:[0,1]
	v_exp_f32_e32 v175, v128
	v_exp_f32_e32 v177, v129
	v_pk_add_f32 v[120:121], v[120:121], v[206:207] op_sel_hi:[1,0] neg_lo:[0,1] neg_hi:[0,1]
	v_exp_f32_e32 v179, v122
	v_exp_f32_e32 v181, v123
	v_pk_add_f32 v[114:115], v[114:115], v[206:207] op_sel_hi:[1,0] neg_lo:[0,1] neg_hi:[0,1]
	v_exp_f32_e32 v183, v124
	v_exp_f32_e32 v185, v125
	v_sub_f32_e32 v1, v116, v206
	v_sub_f32_e32 v212, v117, v206
	v_exp_f32_e32 v172, v118
	v_exp_f32_e32 v174, v119
	v_exp_f32_e32 v176, v120
	v_exp_f32_e32 v178, v121
	v_exp_f32_e32 v180, v114
	v_exp_f32_e32 v182, v115
	v_exp_f32_e32 v184, v1
	v_pk_add_f32 v[170:171], v[146:147], 0 op_sel_hi:[1,0]
	v_add_f32_e32 v1, 0, v211
	v_pk_add_f32 v[170:171], v[148:149], v[170:171]
	v_pk_add_f32 v[186:187], v[172:173], v[0:1]
	v_pk_add_f32 v[170:171], v[158:159], v[170:171]
	v_pk_add_f32 v[186:187], v[174:175], v[186:187]
	v_pk_add_f32 v[170:171], v[160:161], v[170:171]
	v_pk_add_f32 v[186:187], v[176:177], v[186:187]
	v_pk_add_f32 v[170:171], v[162:163], v[170:171]
	v_pk_add_f32 v[186:187], v[178:179], v[186:187]
	v_pk_add_f32 v[170:171], v[164:165], v[170:171]
	v_pk_add_f32 v[186:187], v[180:181], v[186:187]
	v_pk_add_f32 v[170:171], v[166:167], v[170:171]
	v_pk_add_f32 v[186:187], v[182:183], v[186:187]
	v_pk_add_f32 v[170:171], v[168:169], v[170:171]
	v_pk_add_f32 v[186:187], v[184:185], v[186:187]
	s_mov_b64 s[2:3], 0

.LBB0_539:
	v_add_f32_e32 v186, v1, v186
	s_add_i32 s19, s19, 32
	v_pk_add_f32 v[152:153], v[152:153], v[170:171]
	s_waitcnt lgkmcnt(0)
	v_mfma_f32_16x16x32_bf16 v[90:93], v[214:217], v[122:125], v[90:93]
	v_add_f32_e64 v150, v150, v186
	v_add_f32_e64 v151, v151, v187
	v_add_u32_e32 v205, 0xffffff80, v205
	s_cmp_gt_u32 s20, 16
	v_mfma_f32_16x16x32_bf16 v[46:49], v[214:217], v[126:129], v[46:49]
	v_mfma_f32_16x16x32_bf16 v[30:33], v[214:217], v[114:117], v[30:33]
	v_mfma_f32_16x16x32_bf16 v[14:17], v[214:217], v[118:121], v[14:17]
	v_mfma_f32_16x16x32_bf16 v[94:97], v[218:221], v[122:125], v[94:97]
	v_mfma_f32_16x16x32_bf16 v[42:45], v[218:221], v[126:129], v[42:45]
	v_mfma_f32_16x16x32_bf16 v[26:29], v[218:221], v[114:117], v[26:29]
	v_mfma_f32_16x16x32_bf16 v[10:13], v[218:221], v[118:121], v[10:13]
	v_mfma_f32_16x16x32_bf16 v[86:89], v[222:225], v[122:125], v[86:89]
	v_mfma_f32_16x16x32_bf16 v[38:41], v[222:225], v[126:129], v[38:41]
	v_mfma_f32_16x16x32_bf16 v[22:25], v[222:225], v[114:117], v[22:25]
	v_mfma_f32_16x16x32_bf16 v[6:9], v[222:225], v[118:121], v[6:9]
	v_mfma_f32_16x16x32_bf16 v[82:85], v[226:229], v[122:125], v[82:85]
	v_mfma_f32_16x16x32_bf16 v[34:37], v[226:229], v[126:129], v[34:37]
	v_mfma_f32_16x16x32_bf16 v[18:21], v[226:229], v[114:117], v[18:21]
	v_mfma_f32_16x16x32_bf16 v[2:5], v[226:229], v[118:121], v[2:5]
	s_cbranch_scc1 .LBB0_541
	s_waitcnt vmcnt(0)
	v_mov_b64_e32 v[116:117], v[108:109]
	v_mov_b64_e32 v[148:149], v[112:113]
	v_mov_b64_e32 v[120:121], v[100:101]
	v_mov_b64_e32 v[124:125], v[104:105]
	v_mov_b64_e32 v[114:115], v[106:107]
	v_mov_b64_e32 v[146:147], v[110:111]
	v_mov_b64_e32 v[118:119], v[98:99]
	v_mov_b64_e32 v[122:123], v[102:103]
	s_branch .LBB0_525
